# v6 + s_setprio 1/0 around the three MFMA clusters of the FoX attention loop (T5)
# baseline (speedup 1.0000x reference)
.LBB0_551:
	v_sub_f32_e32 v4, v82, v16
	v_exp_f32_e32 v82, v4
	v_sub_f32_e32 v4, v98, v16
	v_sub_f32_e32 v5, v83, v16
	v_exp_f32_e32 v98, v4
	v_exp_f32_e32 v83, v5
	v_sub_f32_e32 v5, v99, v16
	v_exp_f32_e32 v99, v5
	v_add_f32_e32 v4, v82, v98
	v_add_f32_e32 v4, 0, v4
	s_mulk_i32 s34, 0x5000
	v_add_f32_e32 v5, v83, v99
	v_add_f32_e32 v4, v5, v4
	v_sub_f32_e32 v5, v84, v16
	v_exp_f32_e32 v84, v5
	v_sub_f32_e32 v5, v100, v16
	v_exp_f32_e32 v100, v5
	v_cvt_pk_bf16_f32 v8, v98, v99
	s_mov_b64 s[42:43], 0
	v_add_f32_e32 v5, v84, v100
	v_add_f32_e32 v4, v5, v4
	v_sub_f32_e32 v5, v85, v16
	v_exp_f32_e32 v85, v5
	v_sub_f32_e32 v5, v101, v16
	v_exp_f32_e32 v101, v5
	v_cvt_pk_bf16_f32 v163, v84, v85
	v_add_f32_e32 v5, v85, v101
	v_add_f32_e32 v4, v5, v4
	v_sub_f32_e32 v5, v86, v16
	v_exp_f32_e32 v86, v5
	v_sub_f32_e32 v5, v102, v16
	v_exp_f32_e32 v102, v5
	v_cvt_pk_bf16_f32 v9, v100, v101
	v_add_f32_e32 v5, v86, v102
	v_add_f32_e32 v4, v5, v4
	v_sub_f32_e32 v5, v87, v16
	v_exp_f32_e32 v87, v5
	v_sub_f32_e32 v5, v103, v16
	v_exp_f32_e32 v103, v5
	v_cvt_pk_bf16_f32 v164, v86, v87
	v_add_f32_e32 v5, v87, v103
	v_add_f32_e32 v4, v5, v4
	v_sub_f32_e32 v5, v88, v16
	v_exp_f32_e32 v88, v5
	v_sub_f32_e32 v5, v104, v16
	v_exp_f32_e32 v104, v5
	v_cvt_pk_bf16_f32 v10, v102, v103
	v_add_f32_e32 v5, v88, v104
	v_add_f32_e32 v4, v5, v4
	v_sub_f32_e32 v5, v89, v16
	v_exp_f32_e32 v89, v5
	v_sub_f32_e32 v5, v105, v16
	v_exp_f32_e32 v105, v5
	v_cvt_pk_bf16_f32 v165, v88, v89
	v_add_f32_e32 v5, v89, v105
	v_add_f32_e32 v4, v5, v4
	v_sub_f32_e32 v5, v90, v16
	v_exp_f32_e32 v90, v5
	v_sub_f32_e32 v5, v106, v16
	v_exp_f32_e32 v106, v5
	v_cvt_pk_bf16_f32 v11, v104, v105
	v_add_f32_e32 v5, v90, v106
	v_add_f32_e32 v4, v5, v4
	v_sub_f32_e32 v5, v91, v16
	v_exp_f32_e32 v91, v5
	v_sub_f32_e32 v5, v107, v16
	v_exp_f32_e32 v107, v5
	v_cvt_pk_bf16_f32 v12, v90, v91
	v_add_f32_e32 v5, v91, v107
	v_add_f32_e32 v4, v5, v4
	v_sub_f32_e32 v5, v92, v16
	v_exp_f32_e32 v92, v5
	v_sub_f32_e32 v5, v108, v16
	v_exp_f32_e32 v108, v5
	s_nop 0
	v_add_f32_e32 v5, v92, v108
	v_add_f32_e32 v4, v5, v4
	v_sub_f32_e32 v5, v93, v16
	v_exp_f32_e32 v93, v5
	v_sub_f32_e32 v5, v109, v16
	v_exp_f32_e32 v109, v5
	v_cvt_pk_bf16_f32 v13, v92, v93
	v_add_f32_e32 v5, v93, v109
	v_add_f32_e32 v4, v5, v4
	v_sub_f32_e32 v5, v94, v16
	v_exp_f32_e32 v94, v5
	v_sub_f32_e32 v5, v110, v16
	v_exp_f32_e32 v110, v5
	s_nop 0
	v_add_f32_e32 v5, v94, v110
	v_add_f32_e32 v4, v5, v4
	v_sub_f32_e32 v5, v95, v16
	v_exp_f32_e32 v95, v5
	v_sub_f32_e32 v5, v111, v16
	v_exp_f32_e32 v111, v5
	v_cvt_pk_bf16_f32 v14, v94, v95
	v_add_f32_e32 v5, v95, v111
	v_add_f32_e32 v4, v5, v4
	v_sub_f32_e32 v5, v96, v16
	v_exp_f32_e32 v96, v5
	v_sub_f32_e32 v5, v112, v16
	v_exp_f32_e32 v112, v5
	v_cvt_pk_bf16_f32 v6, v110, v111
	v_add_f32_e32 v5, v96, v112
	v_add_f32_e32 v4, v5, v4
	v_sub_f32_e32 v5, v97, v16
	v_exp_f32_e32 v97, v5
	v_sub_f32_e32 v5, v113, v16
	v_exp_f32_e32 v113, v5
	v_cvt_pk_bf16_f32 v15, v96, v97
	v_add_f32_e32 v5, v97, v113
	v_add_f32_e32 v17, v5, v4
	v_fmac_f32_e32 v17, v162, v2
	v_add_u32_e32 v2, s34, v177
	ds_read_b64_tr_b16 v[220:221], v2 offset:34816
	ds_read_b64_tr_b16 v[222:223], v2 offset:37376
	v_cvt_pk_bf16_f32 v162, v82, v83
	v_cvt_pk_bf16_f32 v4, v106, v107
	v_cvt_pk_bf16_f32 v5, v108, v109
	s_waitcnt lgkmcnt(0)
	s_setprio 1
	v_mfma_f32_32x32x16_bf16 v[66:81], v[220:223], v[162:165], v[66:81]
	ds_read_b64_tr_b16 v[220:221], v2 offset:39936
	ds_read_b64_tr_b16 v[222:223], v2 offset:42496
	v_cvt_pk_bf16_f32 v7, v112, v113
	s_waitcnt lgkmcnt(0)
	v_mfma_f32_32x32x16_bf16 v[66:81], v[220:223], v[12:15], v[66:81]
	ds_read_b64_tr_b16 v[220:221], v2 offset:45056
	ds_read_b64_tr_b16 v[222:223], v2 offset:47616
	s_waitcnt lgkmcnt(0)
	v_mfma_f32_32x32x16_bf16 v[66:81], v[220:223], v[8:11], v[66:81]
	ds_read_b64_tr_b16 v[220:221], v2 offset:50176
	ds_read_b64_tr_b16 v[222:223], v2 offset:52736
	s_waitcnt lgkmcnt(0)
	v_mfma_f32_32x32x16_bf16 v[66:81], v[220:223], v[4:7], v[66:81]
	ds_read_b64_tr_b16 v[220:221], v2 offset:34880
	ds_read_b64_tr_b16 v[222:223], v2 offset:37440
	s_waitcnt lgkmcnt(0)
	v_mfma_f32_32x32x16_bf16 v[50:65], v[220:223], v[162:165], v[50:65]
	ds_read_b64_tr_b16 v[220:221], v2 offset:40000
	ds_read_b64_tr_b16 v[222:223], v2 offset:42560
	s_waitcnt lgkmcnt(0)
	v_mfma_f32_32x32x16_bf16 v[50:65], v[220:223], v[12:15], v[50:65]
	ds_read_b64_tr_b16 v[220:221], v2 offset:45120
	ds_read_b64_tr_b16 v[222:223], v2 offset:47680
	s_waitcnt lgkmcnt(0)
	v_mfma_f32_32x32x16_bf16 v[50:65], v[220:223], v[8:11], v[50:65]
	ds_read_b64_tr_b16 v[220:221], v2 offset:50240
	ds_read_b64_tr_b16 v[222:223], v2 offset:52800
	s_waitcnt lgkmcnt(0)
	v_mfma_f32_32x32x16_bf16 v[50:65], v[220:223], v[4:7], v[50:65]
	ds_read_b64_tr_b16 v[220:221], v2 offset:34944
	ds_read_b64_tr_b16 v[222:223], v2 offset:37504
	s_waitcnt lgkmcnt(0)
	v_mfma_f32_32x32x16_bf16 v[34:49], v[220:223], v[162:165], v[34:49]
	ds_read_b64_tr_b16 v[220:221], v2 offset:40064
	ds_read_b64_tr_b16 v[222:223], v2 offset:42624
	s_waitcnt lgkmcnt(0)
	v_mfma_f32_32x32x16_bf16 v[34:49], v[220:223], v[12:15], v[34:49]
	ds_read_b64_tr_b16 v[220:221], v2 offset:45184
	ds_read_b64_tr_b16 v[222:223], v2 offset:47744
	s_waitcnt lgkmcnt(0)
	v_mfma_f32_32x32x16_bf16 v[34:49], v[220:223], v[8:11], v[34:49]
	ds_read_b64_tr_b16 v[220:221], v2 offset:50304
	ds_read_b64_tr_b16 v[222:223], v2 offset:52864
	s_waitcnt lgkmcnt(0)
	v_mfma_f32_32x32x16_bf16 v[34:49], v[220:223], v[4:7], v[34:49]
	ds_read_b64_tr_b16 v[220:221], v2 offset:35008
	ds_read_b64_tr_b16 v[222:223], v2 offset:37568
	s_waitcnt lgkmcnt(0)
	v_mfma_f32_32x32x16_bf16 v[18:33], v[220:223], v[162:165], v[18:33]
	ds_read_b64_tr_b16 v[162:163], v2 offset:40128
	ds_read_b64_tr_b16 v[164:165], v2 offset:42688
	s_waitcnt lgkmcnt(0)
	v_mfma_f32_32x32x16_bf16 v[18:33], v[162:165], v[12:15], v[18:33]
	ds_read_b64_tr_b16 v[12:13], v2 offset:45248
	ds_read_b64_tr_b16 v[14:15], v2 offset:47808
	v_mov_b32_e32 v162, v17
	s_waitcnt lgkmcnt(0)
	v_mfma_f32_32x32x16_bf16 v[18:33], v[12:15], v[8:11], v[18:33]
	ds_read_b64_tr_b16 v[8:9], v2 offset:50368
	ds_read_b64_tr_b16 v[10:11], v2 offset:52928
	s_waitcnt lgkmcnt(0)
	v_mfma_f32_32x32x16_bf16 v[18:33], v[8:11], v[4:7], v[18:33]
	s_setprio 0
	s_add_i32 s34, s49, -1
	s_and_b32 s34, s34, 1
	s_cmp_gt_i32 s50, s51
	s_cbranch_scc0 .LBB0_553
	s_branch .LBB0_562

.LBB0_553:
	s_mul_i32 s35, s34, 0x4400
	v_add_u32_e32 v2, s35, v217
	ds_read_b128 v[4:7], v2 offset:8704
	ds_read_b128 v[8:11], v2
	ds_read_b128 v[12:15], v2 offset:32
	s_add_i32 s35, s50, 63
	s_cmp_le_i32 s35, s38
	s_waitcnt lgkmcnt(2)
	s_setprio 1
	v_mfma_f32_32x32x16_bf16 v[98:113], v[4:7], v[114:117], 0
	ds_read_b128 v[4:7], v2 offset:8736
	s_waitcnt lgkmcnt(2)
	v_mfma_f32_32x32x16_bf16 v[82:97], v[8:11], v[114:117], 0
	s_waitcnt lgkmcnt(1)
	v_mfma_f32_32x32x16_bf16 v[82:97], v[12:15], v[118:121], v[82:97]
	s_waitcnt lgkmcnt(0)
	v_mfma_f32_32x32x16_bf16 v[98:113], v[4:7], v[118:121], v[98:113]
	ds_read_b128 v[4:7], v2 offset:64
	ds_read_b128 v[8:11], v2 offset:8768
	s_waitcnt vmcnt(5) lgkmcnt(1)
	v_mfma_f32_32x32x16_bf16 v[82:97], v[4:7], v[122:125], v[82:97]
	s_waitcnt lgkmcnt(0)
	v_mfma_f32_32x32x16_bf16 v[98:113], v[8:11], v[122:125], v[98:113]
	ds_read_b128 v[4:7], v2 offset:96
	ds_read_b128 v[8:11], v2 offset:8800
	s_waitcnt vmcnt(4) lgkmcnt(1)
	v_mfma_f32_32x32x16_bf16 v[82:97], v[4:7], v[126:129], v[82:97]
	s_waitcnt lgkmcnt(0)
	v_mfma_f32_32x32x16_bf16 v[98:113], v[8:11], v[126:129], v[98:113]
	ds_read_b128 v[4:7], v2 offset:128
	ds_read_b128 v[8:11], v2 offset:8832
	s_waitcnt vmcnt(3) lgkmcnt(1)
	v_mfma_f32_32x32x16_bf16 v[82:97], v[4:7], v[130:133], v[82:97]
	s_waitcnt lgkmcnt(0)
	v_mfma_f32_32x32x16_bf16 v[98:113], v[8:11], v[130:133], v[98:113]
	ds_read_b128 v[4:7], v2 offset:160
	ds_read_b128 v[8:11], v2 offset:8864
	s_waitcnt vmcnt(2) lgkmcnt(1)
	v_mfma_f32_32x32x16_bf16 v[82:97], v[4:7], v[134:137], v[82:97]
	s_waitcnt lgkmcnt(0)
	v_mfma_f32_32x32x16_bf16 v[98:113], v[8:11], v[134:137], v[98:113]
	ds_read_b128 v[4:7], v2 offset:192
	ds_read_b128 v[8:11], v2 offset:8896
	s_waitcnt vmcnt(1) lgkmcnt(1)
	v_mfma_f32_32x32x16_bf16 v[82:97], v[4:7], v[138:141], v[82:97]
	s_waitcnt lgkmcnt(0)
	v_mfma_f32_32x32x16_bf16 v[98:113], v[8:11], v[138:141], v[98:113]
	ds_read_b128 v[4:7], v2 offset:224
	ds_read_b128 v[8:11], v2 offset:8928
	s_waitcnt vmcnt(0) lgkmcnt(1)
	v_mfma_f32_32x32x16_bf16 v[82:97], v[4:7], v[142:145], v[82:97]
	s_waitcnt lgkmcnt(0)
	v_mfma_f32_32x32x16_bf16 v[98:113], v[8:11], v[142:145], v[98:113]
	s_setprio 0
	ds_read_b128 v[4:7], v183 offset:128
	ds_read_b128 v[8:11], v183
	ds_read_b128 v[12:15], v183 offset:32
	ds_read_b128 v[220:223], v183 offset:160
	ds_read_b128 v[224:227], v183 offset:64
	ds_read_b128 v[228:231], v183 offset:192
	ds_read_b128 v[232:235], v183 offset:96
	ds_read_b128 v[236:239], v183 offset:224
	s_waitcnt lgkmcnt(6)
	s_nop 0
	v_pk_fma_f32 v[82:83], v[82:83], s[16:17], v[8:9] op_sel_hi:[1,0,1] neg_lo:[0,0,1] neg_hi:[0,0,1]
	v_pk_fma_f32 v[84:85], v[84:85], s[16:17], v[10:11] op_sel_hi:[1,0,1] neg_lo:[0,0,1] neg_hi:[0,0,1]
	s_waitcnt lgkmcnt(5)
	v_pk_fma_f32 v[86:87], v[86:87], s[16:17], v[12:13] op_sel_hi:[1,0,1] neg_lo:[0,0,1] neg_hi:[0,0,1]
	v_pk_fma_f32 v[88:89], v[88:89], s[16:17], v[14:15] op_sel_hi:[1,0,1] neg_lo:[0,0,1] neg_hi:[0,0,1]
	s_waitcnt lgkmcnt(3)
	v_pk_fma_f32 v[90:91], v[90:91], s[16:17], v[224:225] op_sel_hi:[1,0,1] neg_lo:[0,0,1] neg_hi:[0,0,1]
	v_pk_fma_f32 v[92:93], v[92:93], s[16:17], v[226:227] op_sel_hi:[1,0,1] neg_lo:[0,0,1] neg_hi:[0,0,1]
	s_waitcnt lgkmcnt(0)
	v_pk_fma_f32 v[94:95], v[94:95], s[16:17], v[232:233] op_sel_hi:[1,0,1] neg_lo:[0,0,1] neg_hi:[0,0,1]
	v_pk_fma_f32 v[96:97], v[96:97], s[16:17], v[234:235] op_sel_hi:[1,0,1] neg_lo:[0,0,1] neg_hi:[0,0,1]
	v_pk_fma_f32 v[98:99], v[98:99], s[16:17], v[4:5] op_sel_hi:[1,0,1] neg_lo:[0,0,1] neg_hi:[0,0,1]
	v_pk_fma_f32 v[100:101], v[100:101], s[16:17], v[6:7] op_sel_hi:[1,0,1] neg_lo:[0,0,1] neg_hi:[0,0,1]
	v_pk_fma_f32 v[102:103], v[102:103], s[16:17], v[220:221] op_sel_hi:[1,0,1] neg_lo:[0,0,1] neg_hi:[0,0,1]
	v_pk_fma_f32 v[104:105], v[104:105], s[16:17], v[222:223] op_sel_hi:[1,0,1] neg_lo:[0,0,1] neg_hi:[0,0,1]
	v_pk_fma_f32 v[106:107], v[106:107], s[16:17], v[228:229] op_sel_hi:[1,0,1] neg_lo:[0,0,1] neg_hi:[0,0,1]
	v_pk_fma_f32 v[108:109], v[108:109], s[16:17], v[230:231] op_sel_hi:[1,0,1] neg_lo:[0,0,1] neg_hi:[0,0,1]
	v_pk_fma_f32 v[110:111], v[110:111], s[16:17], v[236:237] op_sel_hi:[1,0,1] neg_lo:[0,0,1] neg_hi:[0,0,1]
	v_pk_fma_f32 v[112:113], v[112:113], s[16:17], v[238:239] op_sel_hi:[1,0,1] neg_lo:[0,0,1] neg_hi:[0,0,1]
	s_cbranch_scc1 .LBB0_557
	v_add_u32_e32 v2, s50, v178
	v_add_u32_e32 v4, 32, v2
	v_cmp_le_i32_e64 s[52:53], v4, v202
	v_add_u32_e32 v4, 33, v2
	v_cmp_le_i32_e64 s[54:55], v4, v202
	v_add_u32_e32 v4, 2, v2
	v_cmp_le_i32_e32 vcc, v2, v202
	v_cndmask_b32_e64 v99, v249, v99, s[54:55]
	v_cmp_le_i32_e64 s[54:55], v4, v202
	v_add_u32_e32 v4, 34, v2
	v_cmp_le_i32_e64 s[56:57], v4, v202
	v_add_u32_e32 v4, 3, v2
	v_cndmask_b32_e64 v98, v249, v98, s[52:53]
	v_cndmask_b32_e64 v100, v249, v100, s[56:57]
	v_cmp_le_i32_e64 s[56:57], v4, v202
	v_add_u32_e32 v4, 35, v2
	v_cmp_le_i32_e64 s[58:59], v4, v202
	v_add_u32_e32 v4, 8, v2
	v_cmp_lt_i32_e64 s[52:53], v2, v202
	v_cndmask_b32_e64 v101, v249, v101, s[58:59]
	v_cmp_le_i32_e64 s[58:59], v4, v202
	v_add_u32_e32 v4, 40, v2
	v_cmp_le_i32_e64 s[60:61], v4, v202
	v_add_u32_e32 v4, 9, v2
	s_nop 0
	v_cndmask_b32_e64 v102, v249, v102, s[60:61]
	v_cmp_le_i32_e64 s[60:61], v4, v202
	v_add_u32_e32 v4, 41, v2
	v_cmp_le_i32_e64 s[62:63], v4, v202
	v_add_u32_e32 v4, 10, v2
	s_nop 0
	v_cndmask_b32_e64 v103, v249, v103, s[62:63]
	v_cmp_le_i32_e64 s[62:63], v4, v202
	v_add_u32_e32 v4, 42, v2
	v_cmp_le_i32_e64 s[64:65], v4, v202
	v_add_u32_e32 v4, 11, v2
	s_nop 0
	v_cndmask_b32_e64 v104, v249, v104, s[64:65]
	v_cmp_le_i32_e64 s[64:65], v4, v202
	v_add_u32_e32 v4, 43, v2
	v_cmp_le_i32_e64 s[66:67], v4, v202
	v_add_u32_e32 v4, 16, v2
	s_nop 0
	v_cndmask_b32_e64 v105, v249, v105, s[66:67]
	v_cmp_le_i32_e64 s[66:67], v4, v202
	v_add_u32_e32 v4, 48, v2
	v_cmp_le_i32_e64 s[68:69], v4, v202
	v_add_u32_e32 v4, 17, v2
	s_nop 0
	v_cndmask_b32_e64 v106, v249, v106, s[68:69]
	v_cmp_le_i32_e64 s[68:69], v4, v202
	v_add_u32_e32 v4, 49, v2
	v_cmp_le_i32_e64 s[70:71], v4, v202
	v_add_u32_e32 v4, 18, v2
	s_nop 0
	v_cndmask_b32_e64 v107, v249, v107, s[70:71]
	v_cmp_le_i32_e64 s[70:71], v4, v202
	v_add_u32_e32 v4, 50, v2
	v_cmp_le_i32_e64 s[72:73], v4, v202
	v_add_u32_e32 v4, 19, v2
	s_nop 0
	v_cndmask_b32_e64 v108, v249, v108, s[72:73]
	v_cmp_le_i32_e64 s[72:73], v4, v202
	v_add_u32_e32 v4, 51, v2
	v_cmp_le_i32_e64 s[74:75], v4, v202
	v_add_u32_e32 v4, 24, v2
	s_nop 0
	v_cndmask_b32_e64 v109, v249, v109, s[74:75]
	v_cmp_le_i32_e64 s[74:75], v4, v202
	v_add_u32_e32 v4, 56, v2
	v_cmp_le_i32_e64 s[76:77], v4, v202
	v_add_u32_e32 v4, 25, v2
	s_nop 0
	v_cndmask_b32_e64 v110, v249, v110, s[76:77]
	v_cmp_le_i32_e64 s[76:77], v4, v202
	v_add_u32_e32 v4, 57, v2
	v_cmp_le_i32_e64 s[78:79], v4, v202
	v_add_u32_e32 v4, 26, v2
	s_nop 0
	v_cndmask_b32_e64 v111, v249, v111, s[78:79]
	v_cmp_le_i32_e64 s[78:79], v4, v202
	v_add_u32_e32 v4, 58, v2
	v_cmp_le_i32_e64 s[80:81], v4, v202
	v_add_u32_e32 v4, 27, v2
	v_add_u32_e32 v2, 59, v2
	v_cndmask_b32_e64 v112, v249, v112, s[80:81]
	v_cmp_le_i32_e64 s[80:81], v4, v202
	v_cmp_gt_i32_e64 s[84:85], v2, v202
	s_and_saveexec_b64 s[44:45], s[84:85]
	v_mov_b32_e32 v113, s21
	s_or_b64 exec, exec, s[44:45]
	v_cndmask_b32_e64 v83, v249, v83, s[52:53]
	v_cndmask_b32_e32 v82, v249, v82, vcc
	v_cndmask_b32_e64 v84, v249, v84, s[54:55]
	v_cndmask_b32_e64 v85, v249, v85, s[56:57]
	v_cndmask_b32_e64 v86, v249, v86, s[58:59]
	v_cndmask_b32_e64 v87, v249, v87, s[60:61]
	v_cndmask_b32_e64 v88, v249, v88, s[62:63]
	v_cndmask_b32_e64 v89, v249, v89, s[64:65]
	v_cndmask_b32_e64 v90, v249, v90, s[66:67]
	v_cndmask_b32_e64 v91, v249, v91, s[68:69]
	v_cndmask_b32_e64 v92, v249, v92, s[70:71]
	v_cndmask_b32_e64 v93, v249, v93, s[72:73]
	v_cndmask_b32_e64 v94, v249, v94, s[74:75]
	v_cndmask_b32_e64 v95, v249, v95, s[76:77]
	v_cndmask_b32_e64 v96, v249, v96, s[78:79]
	v_cndmask_b32_e64 v97, v249, v97, s[80:81]

.LBB0_560:
	v_sub_f32_e32 v4, v82, v203
	v_exp_f32_e32 v82, v4
	v_sub_f32_e32 v4, v98, v203
	v_sub_f32_e32 v5, v83, v203
	v_exp_f32_e32 v98, v4
	v_exp_f32_e32 v83, v5
	v_sub_f32_e32 v5, v99, v203
	v_exp_f32_e32 v99, v5
	v_add_f32_e32 v4, v82, v98
	v_add_f32_e32 v4, 0, v4
	s_mul_i32 s35, s39, 0x5000
	v_add_f32_e32 v5, v83, v99
	v_add_f32_e32 v4, v5, v4
	v_sub_f32_e32 v5, v84, v203
	v_exp_f32_e32 v84, v5
	v_sub_f32_e32 v5, v100, v203
	v_exp_f32_e32 v100, v5
	v_cvt_pk_bf16_f32 v8, v98, v99
	v_add_f32_e32 v5, v84, v100
	v_add_f32_e32 v4, v5, v4
	v_sub_f32_e32 v5, v85, v203
	v_exp_f32_e32 v85, v5
	v_sub_f32_e32 v5, v101, v203
	v_exp_f32_e32 v101, v5
	v_cvt_pk_bf16_f32 v163, v84, v85
	v_add_f32_e32 v5, v85, v101
	v_add_f32_e32 v4, v5, v4
	v_sub_f32_e32 v5, v86, v203
	v_exp_f32_e32 v86, v5
	v_sub_f32_e32 v5, v102, v203
	v_exp_f32_e32 v102, v5
	v_cvt_pk_bf16_f32 v9, v100, v101
	v_add_f32_e32 v5, v86, v102
	v_add_f32_e32 v4, v5, v4
	v_sub_f32_e32 v5, v87, v203
	v_exp_f32_e32 v87, v5
	v_sub_f32_e32 v5, v103, v203
	v_exp_f32_e32 v103, v5
	v_cvt_pk_bf16_f32 v164, v86, v87
	v_add_f32_e32 v5, v87, v103
	v_add_f32_e32 v4, v5, v4
	v_sub_f32_e32 v5, v88, v203
	v_exp_f32_e32 v88, v5
	v_sub_f32_e32 v5, v104, v203
	v_exp_f32_e32 v104, v5
	v_cvt_pk_bf16_f32 v10, v102, v103
	v_add_f32_e32 v5, v88, v104
	v_add_f32_e32 v4, v5, v4
	v_sub_f32_e32 v5, v89, v203
	v_exp_f32_e32 v89, v5
	v_sub_f32_e32 v5, v105, v203
	v_exp_f32_e32 v105, v5
	v_cvt_pk_bf16_f32 v165, v88, v89
	v_add_f32_e32 v5, v89, v105
	v_add_f32_e32 v4, v5, v4
	v_sub_f32_e32 v5, v90, v203
	v_exp_f32_e32 v90, v5
	v_sub_f32_e32 v5, v106, v203
	v_exp_f32_e32 v106, v5
	v_cvt_pk_bf16_f32 v11, v104, v105
	v_add_f32_e32 v5, v90, v106
	v_add_f32_e32 v4, v5, v4
	v_sub_f32_e32 v5, v91, v203
	v_exp_f32_e32 v91, v5
	v_sub_f32_e32 v5, v107, v203
	v_exp_f32_e32 v107, v5
	v_cvt_pk_bf16_f32 v12, v90, v91
	v_add_f32_e32 v5, v91, v107
	v_add_f32_e32 v4, v5, v4
	v_sub_f32_e32 v5, v92, v203
	v_exp_f32_e32 v92, v5
	v_sub_f32_e32 v5, v108, v203
	v_exp_f32_e32 v108, v5
	s_nop 0
	v_add_f32_e32 v5, v92, v108
	v_add_f32_e32 v4, v5, v4
	v_sub_f32_e32 v5, v93, v203
	v_exp_f32_e32 v93, v5
	v_sub_f32_e32 v5, v109, v203
	v_exp_f32_e32 v109, v5
	v_cvt_pk_bf16_f32 v13, v92, v93
	v_add_f32_e32 v5, v93, v109
	v_add_f32_e32 v4, v5, v4
	v_sub_f32_e32 v5, v94, v203
	v_exp_f32_e32 v94, v5
	v_sub_f32_e32 v5, v110, v203
	v_exp_f32_e32 v110, v5
	s_nop 0
	v_add_f32_e32 v5, v94, v110
	v_add_f32_e32 v4, v5, v4
	v_sub_f32_e32 v5, v95, v203
	v_exp_f32_e32 v95, v5
	v_sub_f32_e32 v5, v111, v203
	v_exp_f32_e32 v111, v5
	v_cvt_pk_bf16_f32 v14, v94, v95
	v_add_f32_e32 v5, v95, v111
	v_add_f32_e32 v4, v5, v4
	v_sub_f32_e32 v5, v96, v203
	v_exp_f32_e32 v96, v5
	v_sub_f32_e32 v5, v112, v203
	v_exp_f32_e32 v112, v5
	v_cvt_pk_bf16_f32 v6, v110, v111
	v_add_f32_e32 v5, v96, v112
	v_add_f32_e32 v4, v5, v4
	v_sub_f32_e32 v5, v97, v203
	v_exp_f32_e32 v97, v5
	v_sub_f32_e32 v5, v113, v203
	v_exp_f32_e32 v113, v5
	v_cvt_pk_bf16_f32 v15, v96, v97
	v_add_f32_e32 v5, v97, v113
	v_add_f32_e32 v16, v5, v4
	v_fmac_f32_e32 v16, v162, v2
	v_add_u32_e32 v2, s35, v177
	ds_read_b64_tr_b16 v[220:221], v2 offset:34816
	ds_read_b64_tr_b16 v[222:223], v2 offset:37376
	v_cvt_pk_bf16_f32 v162, v82, v83
	v_cvt_pk_bf16_f32 v4, v106, v107
	v_cvt_pk_bf16_f32 v5, v108, v109
	s_waitcnt lgkmcnt(0)
	s_setprio 1
	v_mfma_f32_32x32x16_bf16 v[66:81], v[220:223], v[162:165], v[66:81]
	ds_read_b64_tr_b16 v[220:221], v2 offset:39936
	ds_read_b64_tr_b16 v[222:223], v2 offset:42496
	v_cvt_pk_bf16_f32 v7, v112, v113
	s_waitcnt lgkmcnt(0)
	v_mfma_f32_32x32x16_bf16 v[66:81], v[220:223], v[12:15], v[66:81]
	ds_read_b64_tr_b16 v[220:221], v2 offset:45056
	ds_read_b64_tr_b16 v[222:223], v2 offset:47616
	s_waitcnt lgkmcnt(0)
	v_mfma_f32_32x32x16_bf16 v[66:81], v[220:223], v[8:11], v[66:81]
	ds_read_b64_tr_b16 v[220:221], v2 offset:50176
	ds_read_b64_tr_b16 v[222:223], v2 offset:52736
	s_waitcnt lgkmcnt(0)
	v_mfma_f32_32x32x16_bf16 v[66:81], v[220:223], v[4:7], v[66:81]
	ds_read_b64_tr_b16 v[220:221], v2 offset:34880
	ds_read_b64_tr_b16 v[222:223], v2 offset:37440
	s_waitcnt lgkmcnt(0)
	v_mfma_f32_32x32x16_bf16 v[50:65], v[220:223], v[162:165], v[50:65]
	ds_read_b64_tr_b16 v[220:221], v2 offset:40000
	ds_read_b64_tr_b16 v[222:223], v2 offset:42560
	s_waitcnt lgkmcnt(0)
	v_mfma_f32_32x32x16_bf16 v[50:65], v[220:223], v[12:15], v[50:65]
	ds_read_b64_tr_b16 v[220:221], v2 offset:45120
	ds_read_b64_tr_b16 v[222:223], v2 offset:47680
	s_waitcnt lgkmcnt(0)
	v_mfma_f32_32x32x16_bf16 v[50:65], v[220:223], v[8:11], v[50:65]
	ds_read_b64_tr_b16 v[220:221], v2 offset:50240
	ds_read_b64_tr_b16 v[222:223], v2 offset:52800
	s_waitcnt lgkmcnt(0)
	v_mfma_f32_32x32x16_bf16 v[50:65], v[220:223], v[4:7], v[50:65]
	ds_read_b64_tr_b16 v[220:221], v2 offset:34944
	ds_read_b64_tr_b16 v[222:223], v2 offset:37504
	s_waitcnt lgkmcnt(0)
	v_mfma_f32_32x32x16_bf16 v[34:49], v[220:223], v[162:165], v[34:49]
	ds_read_b64_tr_b16 v[220:221], v2 offset:40064
	ds_read_b64_tr_b16 v[222:223], v2 offset:42624
	s_waitcnt lgkmcnt(0)
	v_mfma_f32_32x32x16_bf16 v[34:49], v[220:223], v[12:15], v[34:49]
	ds_read_b64_tr_b16 v[220:221], v2 offset:45184
	ds_read_b64_tr_b16 v[222:223], v2 offset:47744
	s_waitcnt lgkmcnt(0)
	v_mfma_f32_32x32x16_bf16 v[34:49], v[220:223], v[8:11], v[34:49]
	ds_read_b64_tr_b16 v[220:221], v2 offset:50304
	ds_read_b64_tr_b16 v[222:223], v2 offset:52864
	s_waitcnt lgkmcnt(0)
	v_mfma_f32_32x32x16_bf16 v[34:49], v[220:223], v[4:7], v[34:49]
	ds_read_b64_tr_b16 v[220:221], v2 offset:35008
	ds_read_b64_tr_b16 v[222:223], v2 offset:37568
	s_waitcnt lgkmcnt(0)
	v_mfma_f32_32x32x16_bf16 v[18:33], v[220:223], v[162:165], v[18:33]
	ds_read_b64_tr_b16 v[162:163], v2 offset:40128
	ds_read_b64_tr_b16 v[164:165], v2 offset:42688
	s_waitcnt lgkmcnt(0)
	v_mfma_f32_32x32x16_bf16 v[18:33], v[162:165], v[12:15], v[18:33]
	ds_read_b64_tr_b16 v[12:13], v2 offset:45248
	ds_read_b64_tr_b16 v[14:15], v2 offset:47808
	v_mov_b32_e32 v162, v16
	s_waitcnt lgkmcnt(0)
	v_mfma_f32_32x32x16_bf16 v[18:33], v[12:15], v[8:11], v[18:33]
	ds_read_b64_tr_b16 v[8:9], v2 offset:50368
	ds_read_b64_tr_b16 v[10:11], v2 offset:52928
	s_waitcnt lgkmcnt(0)
	v_mfma_f32_32x32x16_bf16 v[18:33], v[8:11], v[4:7], v[18:33]
	s_setprio 0
	s_branch .LBB0_563
